# P3 delta items segment (c): the four per-column decay/beta reads also issued once at the segment start
# speedup vs baseline: 1.0027x; 1.0001x over previous
.LBB0_333:
	s_waitcnt lgkmcnt(0)
	s_barrier
	ds_read2st64_b32 v[10:11], v147 offset0:136 offset1:138
	v_add_u32_e32 v18, 64, v147
	ds_read2st64_b32 v[12:13], v18 offset0:136 offset1:138
	v_add_u32_e32 v19, 0x80, v147
	ds_read2st64_b32 v[14:15], v19 offset0:136 offset1:138
	v_add_u32_e32 v18, 0xc0, v147
	ds_read2st64_b32 v[16:17], v18 offset0:136 offset1:138
	ds_read_b128 v[2:5], v148 offset:34816
	ds_read_b128 v[6:9], v148 offset:35328
	ds_read_b128 v[34:37], v213
	ds_read_b128 v[38:41], v213 offset:17408
	ds_read_b128 v[42:45], v214
	ds_read_b128 v[50:53], v214 offset:4352
	ds_read_b128 v[58:61], v214 offset:8704
	ds_read_b128 v[66:69], v214 offset:13056
	s_waitcnt lgkmcnt(3)
	v_mfma_f32_16x16x32_bf16 v[46:49], v[34:37], v[42:45], 0
	v_readlane_b32 s2, v250, 14
	v_readlane_b32 s3, v250, 15
	v_mfma_f32_16x16x32_bf16 v[42:45], v[38:41], v[42:45], 0
	s_waitcnt lgkmcnt(2)
	v_mfma_f32_16x16x32_bf16 v[54:57], v[34:37], v[50:53], 0
	v_mfma_f32_16x16x32_bf16 v[50:53], v[38:41], v[50:53], 0
	s_waitcnt lgkmcnt(1)
	v_mfma_f32_16x16x32_bf16 v[62:65], v[34:37], v[58:61], 0
	v_mfma_f32_16x16x32_bf16 v[58:61], v[38:41], v[58:61], 0
	s_waitcnt lgkmcnt(0)
	v_mfma_f32_16x16x32_bf16 v[34:37], v[34:37], v[66:69], 0
	v_mfma_f32_16x16x32_bf16 v[38:41], v[38:41], v[66:69], 0
	ds_read_b128 v[66:69], v213 offset:64
	ds_read_b128 v[96:99], v213 offset:17472
	ds_read_b128 v[100:103], v214 offset:64
	s_waitcnt lgkmcnt(0)
	v_mfma_f32_16x16x32_bf16 v[46:49], v[66:69], v[100:103], v[46:49]
	v_mfma_f32_16x16x32_bf16 v[42:45], v[96:99], v[100:103], v[42:45]
	ds_read_b128 v[100:103], v214 offset:4416
	s_waitcnt lgkmcnt(0)
	v_mfma_f32_16x16x32_bf16 v[54:57], v[66:69], v[100:103], v[54:57]
	v_mfma_f32_16x16x32_bf16 v[50:53], v[96:99], v[100:103], v[50:53]
	ds_read_b128 v[100:103], v214 offset:8768
	s_waitcnt lgkmcnt(0)
	v_mfma_f32_16x16x32_bf16 v[62:65], v[66:69], v[100:103], v[62:65]
	v_mfma_f32_16x16x32_bf16 v[58:61], v[96:99], v[100:103], v[58:61]
	ds_read_b128 v[100:103], v214 offset:13120
	s_waitcnt lgkmcnt(0)
	v_mfma_f32_16x16x32_bf16 v[34:37], v[66:69], v[100:103], v[34:37]
	v_mfma_f32_16x16x32_bf16 v[38:41], v[96:99], v[100:103], v[38:41]
	ds_read_b128 v[66:69], v213 offset:128
	ds_read_b128 v[96:99], v213 offset:17536
	ds_read_b128 v[100:103], v214 offset:128
	s_waitcnt lgkmcnt(0)
	v_mfma_f32_16x16x32_bf16 v[46:49], v[66:69], v[100:103], v[46:49]
	v_mfma_f32_16x16x32_bf16 v[42:45], v[96:99], v[100:103], v[42:45]
	ds_read_b128 v[100:103], v214 offset:4480
	s_waitcnt lgkmcnt(0)
	v_mfma_f32_16x16x32_bf16 v[54:57], v[66:69], v[100:103], v[54:57]
	v_mfma_f32_16x16x32_bf16 v[50:53], v[96:99], v[100:103], v[50:53]
	ds_read_b128 v[100:103], v214 offset:8832
	s_waitcnt lgkmcnt(0)
	v_mfma_f32_16x16x32_bf16 v[104:107], v[66:69], v[100:103], v[62:65]
	v_mfma_f32_16x16x32_bf16 v[100:103], v[96:99], v[100:103], v[58:61]
	s_nop 2
	ds_read_b128 v[58:61], v214 offset:13184
	s_waitcnt lgkmcnt(0)
	v_mfma_f32_16x16x32_bf16 v[34:37], v[66:69], v[58:61], v[34:37]
	v_mfma_f32_16x16x32_bf16 v[66:69], v[96:99], v[58:61], v[38:41]
	s_nop 2
	ds_read_b128 v[38:41], v213 offset:192
	ds_read_b128 v[96:99], v213 offset:17600
	ds_read_b128 v[58:61], v214 offset:192
	s_waitcnt lgkmcnt(0)
	v_mfma_f32_16x16x32_bf16 v[62:65], v[38:41], v[58:61], v[46:49]
	v_mfma_f32_16x16x32_bf16 v[58:61], v[96:99], v[58:61], v[42:45]
	s_nop 2
	ds_read_b128 v[42:45], v214 offset:4544
	s_waitcnt lgkmcnt(0)
	v_mfma_f32_16x16x32_bf16 v[54:57], v[38:41], v[42:45], v[54:57]
	v_mfma_f32_16x16x32_bf16 v[50:53], v[96:99], v[42:45], v[50:53]
	ds_read_b128 v[42:45], v214 offset:8896
	s_waitcnt lgkmcnt(0)
	v_mfma_f32_16x16x32_bf16 v[46:49], v[38:41], v[42:45], v[104:107]
	v_mfma_f32_16x16x32_bf16 v[42:45], v[96:99], v[42:45], v[100:103]
	s_nop 2
	ds_read_b128 v[100:103], v214 offset:13248
	s_waitcnt lgkmcnt(0)
	v_mfma_f32_16x16x32_bf16 v[38:41], v[38:41], v[100:103], v[34:37]
	v_mfma_f32_16x16x32_bf16 v[34:37], v[96:99], v[100:103], v[66:69]
	v_mov_b32_e32 v96, v10
	v_mov_b32_e32 v97, v11
	s_nop 1
	v_mov_b32_e32 v66, v2
	v_cndmask_b32_e64 v68, 0, 1, s[2:3]
	v_cmp_ne_u32_e64 s[68:69], 1, v68
	s_waitcnt lgkmcnt(0)
	v_sub_f32_e32 v66, v66, v96
	v_mul_f32_e64 v66, |v66|, s51
	v_exp_f32_e32 v67, v66
	v_mov_b32_e32 v66, 0
	s_and_saveexec_b64 s[2:3], s[4:5]
	s_cbranch_execz .LBB0_337
	s_and_b64 vcc, exec, s[68:69]
	v_mov_b32_e32 v66, v97
	s_cbranch_vccnz .LBB0_336
	v_mov_b32_e32 v66, v6

.LBB0_359:
	v_add_u32_e32 v58, 64, v147
	v_mov_b32_e32 v62, v12
	v_mov_b32_e32 v63, v13
	v_mov_b32_e32 v58, v2
	s_waitcnt lgkmcnt(0)
	v_sub_f32_e32 v58, v58, v62
	v_mul_f32_e64 v58, |v58|, s51
	v_exp_f32_e32 v59, v58
	v_mov_b32_e32 v58, 0
	s_and_saveexec_b64 s[2:3], s[12:13]
	s_cbranch_execz .LBB0_363
	s_and_b64 vcc, exec, s[68:69]
	v_mov_b32_e32 v58, v63
	s_cbranch_vccnz .LBB0_362
	v_mov_b32_e32 v58, v6

.LBB0_385:
	v_add_u32_e32 v50, 0x80, v147
	v_mov_b32_e32 v54, v14
	v_mov_b32_e32 v55, v15
	v_mov_b32_e32 v50, v2
	s_waitcnt lgkmcnt(0)
	v_sub_f32_e32 v50, v50, v54
	v_mul_f32_e64 v50, |v50|, s51
	v_exp_f32_e32 v51, v50
	v_mov_b32_e32 v50, 0
	s_and_saveexec_b64 s[2:3], s[20:21]
	s_cbranch_execz .LBB0_389
	s_and_b64 vcc, exec, s[68:69]
	v_mov_b32_e32 v50, v55
	s_cbranch_vccnz .LBB0_388
	v_mov_b32_e32 v50, v6

.LBB0_411:
	v_add_u32_e32 v42, 0xc0, v147
	v_mov_b32_e32 v46, v16
	v_mov_b32_e32 v47, v17
	v_mov_b32_e32 v42, v2
	s_waitcnt lgkmcnt(0)
	v_sub_f32_e32 v42, v42, v46
	v_mul_f32_e64 v42, |v42|, s51
	v_exp_f32_e32 v43, v42
	v_mov_b32_e32 v42, 0
	s_and_saveexec_b64 s[2:3], s[28:29]
	s_cbranch_execz .LBB0_415
	s_and_b64 vcc, exec, s[68:69]
	v_mov_b32_e32 v42, v47
	s_cbranch_vccnz .LBB0_414
	v_mov_b32_e32 v42, v6
